# v32 plus nt cache policy on the diff attention K/V LDS-DMA loads
# speedup vs baseline: 1.0004x; 1.0004x over previous
; DI float bflo(unsigned w) { return __uint_as_float(w << 16); }
; template <int DQK, bool FOX>
; DI void attn_unit(const bf16_t* P, int pitch, int b, int qb, int qcol, int kcol, int vcol, bf16_t* Out, int opitch, int ocol, int gcol, const float* cum, lptr lds) {
;     ...
;     const int tid = tid_(), w = __builtin_amdgcn_readfirstlane(tid >> 6), lane = tid & 63, r = lane & 31, h = lane >> 5;
;     const size_t tokbase = (size_t)b * SEQ;
;     const int q0 = qb * 256 + w * 32;
;     bf16x8 qf[NKS];
; #pragma unroll
;     for (int ks = 0; ks < NKS; ++ks) {
;         u32x4 qw = *(const u32x4*)(P + (tokbase + q0 + r) * pitch + qcol + 16 * ks + 8 * h);
;         if (FOX) { qw.x = pk2(bflo(qw.x) * QC, bfhi(qw.x) * QC); qw.y = pk2(bflo(qw.y) * QC, bfhi(qw.y) * QC); qw.z = pk2(bflo(qw.z) * QC, bfhi(qw.z) * QC); qw.w = pk2(bflo(qw.w) * QC, bfhi(qw.w) * QC); }
;         qf[ks] = __builtin_bit_cast(bf16x8, qw);
;     }
;     const int ntiles = 4 * (qb + 1);
;     f32x16 O[4]; for (int d = 0; d < 4; ++d) O[d] = zero16();
;     float m_run = NEGBIG, l_run = 0.f;
;     float creg = 0.f;
;     size_t kgo[NKD], vgo[2];
; #pragma unroll
;     for (int i = 0; i < NKD; ++i) {
;         int row, c;
;         if (DQK == 128) { row = 4 * (2 * w + i) + (lane >> 4); c = (lane & 15) ^ (row & 15); }
;         else            { row = 8 * w + (lane >> 3);           c = (lane & 7) ^ ((row >> 1) & 7); }
;         kgo[i] = (tokbase + row) * pitch + kcol + c * 8;
;     }
; #pragma unroll
;     for (int i = 0; i < 2; ++i) { const int row = 4 * (2 * w + i) + (lane >> 4), c = (lane & 15) ^ (4 * (row & 3)); vgo[i] = (tokbase + row) * pitch + vcol + c * 8; }
;     int kx[NKS], vx[4];
; #pragma unroll
;     for (int ks = 0; ks < NKS; ++ks) kx[ks] = (DQK == 128) ? (r * 256 + (((2 * ks + h) ^ (r & 15)) << 4)) : (r * 128 + (((2 * ks + h) ^ ((r >> 1) & 7)) << 4));
;     { const int q4 = (lane & 15) >> 2, p4 = lane & 3, g1 = (lane >> 4) & 1;
; #pragma unroll
;       for (int d = 0; d < 4; ++d) vx[d] = (4 * h + q4) * 256 + ((4 * (d ^ q4) + 2 * g1 + (p4 >> 1)) << 4) + ((p4 & 1) << 3); }
;     const int cfo = 16 * h;
;     ...
;     dma(ntiles - 1, std::integral_constant<int, 0>{});
;     if (FOX) { if (tid < 64) lst<float>(lds, OFF_C + tid * 4, -cum[(ntiles - 1) * 64 + tid] * LOG2E); }
;     asm volatile("s_waitcnt vmcnt(0)" ::: "memory");
;     __syncthreads();
.LBB0_529:
	s_or_b64 exec, exec, s[2:3]
	v_mov_b32_e32 v0, s87
	s_waitcnt lgkmcnt(0)
	s_barrier
	ds_read_b32 v0, v0
	s_movk_i32 s2, 0x41f
	s_waitcnt lgkmcnt(0)
	v_cmp_lt_i32_e32 vcc, s2, v0
	v_readfirstlane_b32 s40, v0
	s_mov_b64 s[2:3], -1
	s_cbranch_vccnz .LBB0_524
	s_cmp_gt_i32 s40, 31
	s_cbranch_scc0 .LBB0_552
	s_sub_i32 s3, s40, 32
	v_mov_b32_e32 v8, v194
	s_lshr_b32 s18, s3, 6
	s_sub_i32 s16, 15, s18
	v_readfirstlane_b32 s10, v8
	s_ashr_i32 s14, s10, 6
	s_lshl_b32 s3, s3, 9
	s_and_b32 s12, s3, 0x7000
	s_lshl_b32 s3, s16, 8
	s_lshl_b32 s10, s14, 5
	s_lshl_b32 s2, s40, 6
	s_add_i32 s3, s10, s3
	s_and_b32 s2, s2, 0x180
	s_ashr_i32 s10, s3, 31
	v_and_b32_e32 v9, 31, v8
	s_add_u32 s11, s3, s12
	v_or_b32_e32 v0, s11, v9
	v_mov_b64_e32 v[2:3], s[4:5]
	s_addc_u32 s13, s10, 0
	v_mad_u64_u32 v[114:115], s[10:11], v0, s95, v[2:3]
	s_lshl_b32 s10, s40, 7
	v_bfe_u32 v10, v8, 5, 1
	v_mad_i32_i24 v115, s13, v208, v115
	s_and_b32 s82, s10, 0x380
	v_lshl_add_u64 v[4:5], v[114:115], 0, s[82:83]
	v_lshlrev_b32_e32 v0, 4, v10
	v_lshl_add_u64 v[4:5], v[4:5], 0, v[0:1]
	s_mov_b64 s[10:11], 0x1000
	v_lshl_add_u64 v[6:7], v[4:5], 0, s[10:11]
	s_movk_i32 s10, 0x1000
	v_add_co_u32_e32 v4, vcc, s10, v4
	s_lshl_b32 s10, s14, 3
	v_bfe_u32 v0, v8, 3, 3
	v_or_b32_e32 v0, s10, v0
	v_addc_co_u32_e32 v5, vcc, 0, v5, vcc
	global_load_dwordx4 v[98:101], v[6:7], off offset:32
	global_load_dwordx4 v[102:105], v[6:7], off offset:64
	global_load_dwordx4 v[106:109], v[4:5], off
	global_load_dwordx4 v[110:113], v[6:7], off offset:96
	v_lshrrev_b32_e32 v4, 1, v0
	v_xor_b32_e32 v6, v4, v8
	v_bfe_u32 v4, v8, 4, 2
	v_or_b32_e32 v5, s10, v4
	v_lshlrev_b32_e32 v4, 5, v4
	v_lshlrev_b32_e32 v7, 3, v8
	s_movk_i32 s10, 0x78
	v_add_u32_e32 v0, s12, v0
	v_bitop3_b32 v4, v4, v7, s10 bitop3:0x78
	v_or_b32_e32 v11, s2, v4
	v_add_u32_e32 v12, s12, v5
	v_mad_i64_i32 v[4:5], s[10:11], v0, s95, v[2:3]
	v_lshlrev_b32_e32 v0, 4, v6
	v_lshl_add_u64 v[4:5], v[4:5], 0, s[82:83]
	v_and_b32_e32 v0, 0x70, v0
	v_lshl_add_u64 v[4:5], v[4:5], 0, v[0:1]
	s_mov_b64 s[10:11], 0x1400
	s_mul_i32 s12, s16, 0x1c0000
	v_lshl_add_u64 v[116:117], v[4:5], 0, s[10:11]
	s_lshl_b32 s10, s14, 10
	s_add_i32 s82, s12, 0x150000
	s_add_i32 s10, s10, 0
	v_lshl_add_u64 v[4:5], v[116:117], 0, s[82:83]
	s_mov_b32 m0, s10
	s_lshl_b32 s11, s14, 11
	v_or_b32_e32 v13, 4, v12
	global_load_lds_dwordx4 v[4:5], off nt
	v_mad_i64_i32 v[4:5], s[12:13], v12, s95, v[2:3]
	v_lshl_or_b32 v0, v11, 1, v209
	s_add_i32 s11, s11, 0
	v_lshl_add_u64 v[118:119], v[4:5], 0, v[0:1]
	s_add_i32 s12, s11, 0x2000
	v_mad_i64_i32 v[2:3], s[14:15], v13, s95, v[2:3]
	v_lshl_add_u64 v[4:5], v[118:119], 0, s[82:83]
	s_mov_b32 m0, s12
	v_lshl_add_u64 v[120:121], v[2:3], 0, v[0:1]
	s_add_i32 s13, s11, 0x2400
	global_load_lds_dwordx4 v[4:5], off nt
	v_lshl_add_u64 v[2:3], v[120:121], 0, s[82:83]
	s_mov_b32 m0, s13
	v_lshlrev_b32_e32 v0, 7, v9
	global_load_lds_dwordx4 v[2:3], off nt
	v_lshrrev_b32_e32 v2, 1, v8
	v_bfe_u32 v3, v8, 1, 3
	v_bitop3_b32 v2, v10, v2, 7 bitop3:0x78
	v_lshl_or_b32 v123, v2, 4, v0
	v_bitop3_b32 v2, v10, v3, 2 bitop3:0x36
	v_lshl_or_b32 v124, v2, 4, v0
	v_bitop3_b32 v2, v10, v3, 4 bitop3:0x36
	v_lshl_or_b32 v125, v2, 4, v0
	v_bitop3_b32 v2, v10, v3, 6 bitop3:0x36
	v_lshl_or_b32 v126, v2, 4, v0
	v_bfe_u32 v0, v8, 2, 2
	v_lshrrev_b32_e32 v4, 3, v8
	v_bfe_u32 v5, v8, 1, 1
	v_lshlrev_b32_e32 v2, 10, v10
	v_lshlrev_b32_e32 v3, 8, v0
	v_and_or_b32 v4, v4, 2, v5
	v_and_b32_e32 v5, 8, v7
	v_lshlrev_b32_e32 v0, 6, v0
	s_lshl_b32 s15, s16, 2
	v_or3_b32 v2, v2, v3, v5
	v_lshl_or_b32 v0, v4, 4, v0
	s_movk_i32 s16, 0xc0
	v_mov_b32_e32 v14, v1
	v_mov_b32_e32 v15, v1
	v_or_b32_e32 v127, v0, v2
	v_bitop3_b32 v128, v0, 64, v2 bitop3:0x36
	v_bitop3_b32 v129, v0, s29, v2 bitop3:0x36
	v_bitop3_b32 v130, v0, s16, v2 bitop3:0x36
	s_waitcnt vmcnt(0)
	v_lshlrev_b32_e32 v122, 2, v10
	v_or_b32_e32 v131, s3, v9
	v_mov_b32_e32 v0, v1
	v_mov_b32_e32 v2, v1
	v_mov_b32_e32 v3, v1
	v_mov_b32_e32 v4, v1
	v_mov_b32_e32 v5, v1
	v_mov_b32_e32 v6, v1
	v_mov_b32_e32 v7, v1
	v_mov_b32_e32 v8, v1
	v_mov_b32_e32 v9, v1
	v_mov_b32_e32 v10, v1
	v_mov_b32_e32 v11, v1
	v_mov_b32_e32 v12, v1
	v_mov_b32_e32 v13, v1
	v_mov_b64_e32 v[64:65], v[14:15]
	v_mov_b64_e32 v[48:49], v[14:15]
	v_mov_b64_e32 v[32:33], v[14:15]
	s_lshl_b32 s17, s18, 2
	s_lshl_b32 s18, s18, 8
	v_mov_b64_e32 v[62:63], v[12:13]
	v_mov_b64_e32 v[60:61], v[10:11]
	v_mov_b64_e32 v[58:59], v[8:9]
	v_mov_b64_e32 v[56:57], v[6:7]
	v_mov_b64_e32 v[54:55], v[4:5]
	v_mov_b64_e32 v[52:53], v[2:3]
	v_mov_b64_e32 v[50:51], v[0:1]
	v_mov_b64_e32 v[46:47], v[12:13]
	v_mov_b64_e32 v[44:45], v[10:11]
	v_mov_b64_e32 v[42:43], v[8:9]
	v_mov_b64_e32 v[40:41], v[6:7]
	v_mov_b64_e32 v[38:39], v[4:5]
	v_mov_b64_e32 v[36:37], v[2:3]
	v_mov_b64_e32 v[34:35], v[0:1]
	v_mov_b64_e32 v[30:31], v[12:13]
	v_mov_b64_e32 v[28:29], v[10:11]
	v_mov_b64_e32 v[26:27], v[8:9]
	v_mov_b64_e32 v[24:25], v[6:7]
	v_mov_b64_e32 v[22:23], v[4:5]
	v_mov_b64_e32 v[20:21], v[2:3]
	v_mov_b64_e32 v[18:19], v[0:1]
	v_mov_b64_e32 v[16:17], v[14:15]
	s_mov_b32 s14, 0
	s_add_i32 s15, s15, 4
	s_or_b32 s16, s3, 31
	s_sub_i32 s17, 62, s17
	s_sub_i32 s18, 0xfff, s18
	v_mov_b32_e32 v133, 0xf149f2ca
	v_mov_b32_e32 v132, 0
	v_mov_b64_e32 v[14:15], v[12:13]
	v_mov_b64_e32 v[12:13], v[10:11]
	v_mov_b64_e32 v[10:11], v[8:9]
	v_mov_b64_e32 v[8:9], v[6:7]
	v_mov_b64_e32 v[6:7], v[4:5]
	v_mov_b64_e32 v[4:5], v[2:3]
	v_mov_b64_e32 v[2:3], v[0:1]
	s_waitcnt vmcnt(0) lgkmcnt(0)
	s_barrier
	s_branch .LBB0_534

; #define LAS __attribute__((address_space(3)))
; template <int DQK, bool FOX>
; DI void attn_unit(const bf16_t* P, int pitch, int b, int qb, int qcol, int kcol, int vcol, bf16_t* Out, int opitch, int ocol, int gcol, const float* cum, lptr lds) {
;     ...
;     auto dma = [&](int kt, auto BUFC) {
;         constexpr int buf = decltype(BUFC)::value;
;         const size_t step = (size_t)kt * 64 * pitch;
; #pragma unroll
;         for (int i = 0; i < NKD; ++i) __builtin_amdgcn_global_load_lds((const unsigned*)(P + kgo[i] + step), (LAS unsigned*)(lds + OFF_K + buf * REG + (NKD * w + i) * 1024), 16, 0, 0);
; #pragma unroll
;         for (int i = 0; i < 2; ++i) __builtin_amdgcn_global_load_lds((const unsigned*)(P + vgo[i] + step), (LAS unsigned*)(lds + OFF_V + buf * REG + (2 * w + i) * 1024), 16, 0, 0);
;     };
.LBB0_534:
	s_add_i32 s19, s17, 1
	s_cmp_lt_i32 s19, 1
	s_cbranch_scc1 .LBB0_536
	v_mad_u64_u32 v[66:67], s[26:27], s17, v210, v[116:117]
	s_add_i32 m0, s10, 0x6000
	s_nop 0
	global_load_lds_dwordx4 v[66:67], off nt
	v_mad_u64_u32 v[66:67], s[26:27], s17, v210, v[118:119]
	s_add_i32 m0, s11, 0x8000
	s_nop 0
	global_load_lds_dwordx4 v[66:67], off nt
	v_mad_u64_u32 v[66:67], s[26:27], s17, v210, v[120:121]
	s_add_i32 m0, s11, 0x8400
	s_nop 0
	global_load_lds_dwordx4 v[66:67], off nt

; #define LAS __attribute__((address_space(3)))
; template <int DQK, bool FOX>
; DI void attn_unit(const bf16_t* P, int pitch, int b, int qb, int qcol, int kcol, int vcol, bf16_t* Out, int opitch, int ocol, int gcol, const float* cum, lptr lds) {
;     ...
;     auto dma = [&](int kt, auto BUFC) {
;         constexpr int buf = decltype(BUFC)::value;
;         const size_t step = (size_t)kt * 64 * pitch;
; #pragma unroll
;         for (int i = 0; i < NKD; ++i) __builtin_amdgcn_global_load_lds((const unsigned*)(P + kgo[i] + step), (LAS unsigned*)(lds + OFF_K + buf * REG + (NKD * w + i) * 1024), 16, 0, 0);
; #pragma unroll
;         for (int i = 0; i < 2; ++i) __builtin_amdgcn_global_load_lds((const unsigned*)(P + vgo[i] + step), (LAS unsigned*)(lds + OFF_V + buf * REG + (2 * w + i) * 1024), 16, 0, 0);
;     };
;     auto body = [&](int it, auto BUFC) {
;         constexpr int buf = decltype(BUFC)::value;
;         const int kt = ntiles - 1 - it;
;         const bool more = (kt > 0);
;         if (more) { dma(kt - 1, std::integral_constant<int, 1 - buf>{}); if (FOX) { if (tid < 64) creg = -cum[(kt - 1) * 64 + tid] * LOG2E; } }
;     ...
;         asm volatile("s_waitcnt vmcnt(0)" ::: "memory");
;         __syncthreads();
.LBB0_543:
	s_waitcnt vmcnt(0)
	s_xor_b32 s19, s14, -2
	s_add_i32 s19, s19, s15
	s_cmp_lt_i32 s19, 1
	s_waitcnt vmcnt(0) lgkmcnt(0)
	s_barrier
	s_cbranch_scc1 .LBB0_545
	s_add_i32 s20, s19, -1
	s_mov_b32 m0, s10
	v_mad_u64_u32 v[66:67], s[26:27], s20, v210, v[116:117]
	global_load_lds_dwordx4 v[66:67], off nt
	v_mad_u64_u32 v[66:67], s[26:27], s20, v210, v[118:119]
	s_mov_b32 m0, s12
	s_nop 0
	global_load_lds_dwordx4 v[66:67], off nt
	v_mad_u64_u32 v[66:67], s[26:27], s20, v210, v[120:121]
	s_mov_b32 m0, s13
	s_nop 0
	global_load_lds_dwordx4 v[66:67], off nt
